# P1 de-phasing delay 6.8 us (2 x s_sleep 127) instead of 10 us
# speedup vs baseline: 1.0037x; 1.0037x over previous
.LBB0_107:
	v_writelane_b32 v254, s59, 20
	v_writelane_b32 v254, s60, 21
	s_nop 1
	v_writelane_b32 v254, s61, 22
	s_or_b64 exec, exec, s[0:1]
	s_add_u32 s56, s90, 0x5f6ea00
	s_addc_u32 s57, s91, 0
	s_add_u32 s40, s90, 0x3eeea00
	s_addc_u32 s41, s91, 0
	s_add_u32 s96, s90, 0x6faea00
	s_addc_u32 s97, s91, 0
	s_add_u32 s0, s90, 0x7feea00
	s_addc_u32 s1, s91, 0
	v_writelane_b32 v254, s0, 23
	v_mov_b32_e32 v12, v0
	s_waitcnt lgkmcnt(0)
	v_writelane_b32 v254, s1, 24
	s_add_u32 s0, s90, 0x902ea00
	s_addc_u32 s1, s91, 0
	v_writelane_b32 v254, s0, 25
	s_add_u32 s94, s90, 0x1e6ea00
	s_addc_u32 s95, s91, 0
	v_writelane_b32 v254, s1, 26
	s_barrier
	v_readlane_b32 s27, v254, 20
	s_bitcmp0_b32 s27, 3
	s_cbranch_scc1 .Lstg1_done
	s_sleep 127
	s_sleep 127
.Lstg1_done:
	s_cmpk_lt_i32 s27, 0x100
	s_cselect_b64 s[0:1], -1, 0
	v_writelane_b32 v254, s0, 27
	s_cmpk_gt_i32 s27, 0xff
	s_nop 0
	v_writelane_b32 v254, s1, 28
	s_cbranch_scc1 .LBB0_165
	v_ashrrev_i32_e32 v8, 6, v12
	v_lshlrev_b32_e32 v2, 7, v8
	v_ashrrev_i32_e32 v3, 31, v2
	v_lshlrev_b64 v[6:7], 1, v[2:3]
	s_movk_i32 s0, 0x3000
	v_lshl_add_u64 v[4:5], s[94:95], 0, v[6:7]
	v_and_b32_e32 v2, 48, v12
	v_mov_b32_e32 v3, 0
	v_lshl_add_u64 v[6:7], s[90:91], 0, v[6:7]
	v_mul_lo_u32 v8, v8, s0
	s_mov_b32 s5, 0x2aaaaaab
	v_lshl_add_u64 v[4:5], v[4:5], 0, v[2:3]
	v_lshl_add_u64 v[6:7], v[6:7], 0, v[2:3]
	v_add3_u32 v2, 16, v8, v2
	v_mul_hi_i32 v8, v12, s5
	v_lshrrev_b32_e32 v10, 31, v8
	v_ashrrev_i32_e32 v8, 3, v8
	v_add_u32_e32 v11, v8, v10
	v_mul_lo_u32 v8, v11, 48
	s_movk_i32 s4, 0x180
	v_sub_u32_e32 v8, v12, v8
	v_lshlrev_b32_e32 v13, 1, v8
	v_mul_lo_u32 v10, v11, s4
	v_lshlrev_b32_e32 v8, 3, v8
	v_add3_u32 v24, 16, v10, v8
	v_add_u32_e32 v10, 0x200, v12
	v_mul_hi_i32 v15, v10, s5
	v_lshrrev_b32_e32 v16, 31, v15
	v_ashrrev_i32_e32 v15, 3, v15
	v_add_u32_e32 v27, v15, v16
	v_mul_lo_u32 v15, v27, 48
	v_sub_u32_e32 v10, v10, v15
	v_and_b32_e32 v9, 15, v12
	v_lshlrev_b32_e32 v28, 1, v10
	v_mul_lo_u32 v15, v27, s4
	v_lshlrev_b32_e32 v10, 3, v10
	v_add_u32_e32 v12, 0x400, v12
	s_add_u32 s0, s80, 0xd0
	v_add3_u32 v29, 16, v15, v10
	v_mul_hi_i32 v15, v12, s5
	s_addc_u32 s1, s81, 0
	v_lshrrev_b32_e32 v16, 31, v15
	v_ashrrev_i32_e32 v15, 3, v15
	v_add_u32_e32 v32, v15, v16
	s_add_u32 s10, s88, 0x829c000
	v_mul_lo_u32 v15, v32, 48
	s_addc_u32 s11, s89, 0
	v_sub_u32_e32 v12, v12, v15
	s_add_u32 s12, s88, 0x821c000
	v_lshlrev_b32_e32 v33, 1, v12
	v_mul_lo_u32 v15, v32, s4
	v_lshlrev_b32_e32 v12, 3, v12
	s_addc_u32 s13, s89, 0
	v_mul_u32_u24_e32 v14, 0x180, v9
	v_and_b32_e32 v8, 15, v11
	v_and_b32_e32 v10, 15, v27
	v_add3_u32 v34, 16, v15, v12
	v_and_b32_e32 v12, 15, v32
	s_add_u32 s14, s88, 0x871e000
	v_add_u32_e32 v25, 0x12000, v24
	v_add_u32_e32 v26, 0x15000, v24
	v_cmp_lt_u32_e64 s[2:3], 12, v8
	v_add_u32_e32 v8, -13, v8
	v_add_u32_e32 v30, 0x12000, v29
	v_add_u32_e32 v31, 0x15000, v29
	v_cmp_lt_u32_e64 s[6:7], 12, v10
	v_add_u32_e32 v10, -13, v10
	v_add_u32_e32 v35, 0x12000, v34
	v_add_u32_e32 v36, 0x15000, v34
	v_cmp_lt_u32_e64 s[8:9], 12, v12
	v_add_u32_e32 v12, -13, v12
	s_addc_u32 s15, s89, 0
	s_mov_b32 s4, 0x8000
	v_add_u32_e32 v37, v2, v14
	s_movk_i32 s5, 0x1ff
	s_movk_i32 s24, 0x5ff
	s_movk_i32 s25, 0x7ff
	s_movk_i32 s26, 0x9ff
	s_branch .LBB0_110
